# conv_sample_kv K part with 16-byte stores (8 d per lane), plus loop-head alignment
# baseline (speedup 1.0000x reference)
; __device__ __forceinline__ float ldnt(const float* p) { return __builtin_nontemporal_load(p); }
; __device__ __forceinline__ float4 ldnt4(const float* p) { const f32x4 v = __builtin_nontemporal_load((const f32x4*)p); return make_float4(v[0], v[1], v[2], v[3]); }
; __device__ __forceinline__ void conv_sample_kv(KP p, int l) {
;     ...
;     for (size_t i0 = gt; i0 < (size_t)128 * 256 * 64; i0 += 4 * gs) {
;         float4 v[4];
; #pragma unroll
;         for (int u = 0; u < 4; ++u) { const size_t i = i0 + u * gs; if (i < (size_t)128 * 256 * 64) v[u] = ldnt4(ck + i * 4); }
; #pragma unroll
;         for (int u = 0; u < 4; ++u) {
;             const size_t i = i0 + u * gs;
;             if (i < (size_t)128 * 256 * 64) {
;                 const int d4 = i & 15, h = (i >> 4) & 3, key = (i >> 6) & 255, b = (int)(i >> 14);
;                 *(uint2*)(Ks + ((size_t)(b * 4 + h) * 256 + key) * 64 + d4 * 4) = make_uint2(pack2(v[u].x, v[u].y), pack2(v[u].z, v[u].w));
;             }
;         }
;     ...
;     for (size_t i0 = gt; i0 < (size_t)128 * 64 * 256; i0 += 4 * gs) {
;         float v[4][4];
; #pragma unroll
;         for (int u = 0; u < 4; ++u) {
;             const size_t i = i0 + u * gs;
;             if (i < (size_t)128 * 64 * 256) {
;                 const int d = i & 63, h = (i >> 6) & 3, kq = (i >> 8) & 63, b = (int)(i >> 14);
; #pragma unroll
;                 for (int j = 0; j < 4; ++j) v[u][j] = ldnt(cv + ((size_t)(b * 256 + kq * 4 + j) * 4 + h) * 64 + d);
;             }
;         }
; #pragma unroll
;         for (int u = 0; u < 4; ++u) {
;             const size_t i = i0 + u * gs;
;             if (i < (size_t)128 * 64 * 256) {
;                 const int d = i & 63, h = (i >> 6) & 3, kq = (i >> 8) & 63, b = (int)(i >> 14);
;                 *(uint2*)(Vts + ((size_t)(b * 4 + h) * 64 + d) * 256 + kq * 4) = make_uint2(pack2(v[u][0], v[u][1]), pack2(v[u][2], v[u][3]));
;             }
;         }
.Lconv_pair:
	s_lshr_b32 s2, s24, 2
	s_lshl_b32 s2, s2, 18
	s_and_b32 s11, s24, 3
	s_lshl_b32 s11, s11, 8
	s_or_b32 s2, s2, s11
	s_add_u32 s40, s44, s2
	s_addc_u32 s41, s45, 0
	s_add_u32 s42, s46, s2
	s_addc_u32 s43, s47, 0
	s_lshl_b32 s2, s24, 15
	s_add_u32 s48, s58, 0x3f20000
	s_addc_u32 s49, s59, 0
	s_add_u32 s48, s48, s2
	s_addc_u32 s49, s49, 0
	s_add_u32 s50, s58, 0x4f20000
	s_addc_u32 s51, s59, 0
	s_add_u32 s50, s50, s2
	s_addc_u32 s51, s51, 0
	s_mov_b64 s[52:53], s[40:41]
	s_mov_b64 s[54:55], s[48:49]
	v_and_b32_e32 v250, 7, v192
	v_lshrrev_b32_e32 v251, 3, v192
	v_lshlrev_b32_e32 v236, 5, v250
	v_lshl_add_u32 v236, v251, 10, v236
	v_lshlrev_b32_e32 v237, 4, v250
	v_lshl_add_u32 v237, v251, 7, v237
	global_load_dwordx4 v[0:3], v236, s[52:53] nt
	global_load_dwordx4 v[4:7], v236, s[52:53] offset:16 nt
	s_add_u32 s52, s52, 0x8000
	s_addc_u32 s53, s53, 0
	global_load_dwordx4 v[8:11], v236, s[52:53] nt
	global_load_dwordx4 v[14:17], v236, s[52:53] offset:16 nt
	s_add_u32 s52, s52, 0x8000
	s_addc_u32 s53, s53, 0
	global_load_dwordx4 v[18:21], v236, s[52:53] nt
	global_load_dwordx4 v[22:25], v236, s[52:53] offset:16 nt
	s_add_u32 s52, s52, 0x8000
	s_addc_u32 s53, s53, 0
	global_load_dwordx4 v[26:29], v236, s[52:53] nt
	global_load_dwordx4 v[30:33], v236, s[52:53] offset:16 nt
	s_add_u32 s52, s52, 0x8000
	s_addc_u32 s53, s53, 0
	s_waitcnt vmcnt(6)
	v_cvt_pk_bf16_f32 v242, v0, v1
	v_cvt_pk_bf16_f32 v243, v2, v3
	v_cvt_pk_bf16_f32 v244, v4, v5
	v_cvt_pk_bf16_f32 v245, v6, v7
	global_store_dwordx4 v237, v[242:245], s[54:55]
	s_add_u32 s54, s54, 0x1000
	s_addc_u32 s55, s55, 0
	s_waitcnt vmcnt(5)
	v_cvt_pk_bf16_f32 v246, v8, v9
	v_cvt_pk_bf16_f32 v247, v10, v11
	v_cvt_pk_bf16_f32 v248, v14, v15
	v_cvt_pk_bf16_f32 v249, v16, v17
	global_store_dwordx4 v237, v[246:249], s[54:55]
	s_add_u32 s54, s54, 0x1000
	s_addc_u32 s55, s55, 0
	s_waitcnt vmcnt(4)
	v_cvt_pk_bf16_f32 v242, v18, v19
	v_cvt_pk_bf16_f32 v243, v20, v21
	v_cvt_pk_bf16_f32 v244, v22, v23
	v_cvt_pk_bf16_f32 v245, v24, v25
	global_store_dwordx4 v237, v[242:245], s[54:55]
	s_add_u32 s54, s54, 0x1000
	s_addc_u32 s55, s55, 0
	s_waitcnt vmcnt(3)
	v_cvt_pk_bf16_f32 v246, v26, v27
	v_cvt_pk_bf16_f32 v247, v28, v29
	v_cvt_pk_bf16_f32 v248, v30, v31
	v_cvt_pk_bf16_f32 v249, v32, v33
	global_store_dwordx4 v237, v[246:249], s[54:55]
	s_add_u32 s54, s54, 0x1000
	s_addc_u32 s55, s55, 0
	global_load_dwordx4 v[0:3], v236, s[52:53] nt
	global_load_dwordx4 v[4:7], v236, s[52:53] offset:16 nt
	s_add_u32 s52, s52, 0x8000
	s_addc_u32 s53, s53, 0
	global_load_dwordx4 v[8:11], v236, s[52:53] nt
	global_load_dwordx4 v[14:17], v236, s[52:53] offset:16 nt
	s_add_u32 s52, s52, 0x8000
	s_addc_u32 s53, s53, 0
	global_load_dwordx4 v[18:21], v236, s[52:53] nt
	global_load_dwordx4 v[22:25], v236, s[52:53] offset:16 nt
	s_add_u32 s52, s52, 0x8000
	s_addc_u32 s53, s53, 0
	global_load_dwordx4 v[26:29], v236, s[52:53] nt
	global_load_dwordx4 v[30:33], v236, s[52:53] offset:16 nt
	s_add_u32 s52, s52, 0x8000
	s_addc_u32 s53, s53, 0
	s_waitcnt vmcnt(6)
	v_cvt_pk_bf16_f32 v242, v0, v1
	v_cvt_pk_bf16_f32 v243, v2, v3
	v_cvt_pk_bf16_f32 v244, v4, v5
	v_cvt_pk_bf16_f32 v245, v6, v7
	global_store_dwordx4 v237, v[242:245], s[54:55]
	s_add_u32 s54, s54, 0x1000
	s_addc_u32 s55, s55, 0
	s_waitcnt vmcnt(5)
	v_cvt_pk_bf16_f32 v246, v8, v9
	v_cvt_pk_bf16_f32 v247, v10, v11
	v_cvt_pk_bf16_f32 v248, v14, v15
	v_cvt_pk_bf16_f32 v249, v16, v17
	global_store_dwordx4 v237, v[246:249], s[54:55]
	s_add_u32 s54, s54, 0x1000
	s_addc_u32 s55, s55, 0
	s_waitcnt vmcnt(4)
	v_cvt_pk_bf16_f32 v242, v18, v19
	v_cvt_pk_bf16_f32 v243, v20, v21
	v_cvt_pk_bf16_f32 v244, v22, v23
	v_cvt_pk_bf16_f32 v245, v24, v25
	global_store_dwordx4 v237, v[242:245], s[54:55]
	s_add_u32 s54, s54, 0x1000
	s_addc_u32 s55, s55, 0
	s_waitcnt vmcnt(3)
	v_cvt_pk_bf16_f32 v246, v26, v27
	v_cvt_pk_bf16_f32 v247, v28, v29
	v_cvt_pk_bf16_f32 v248, v30, v31
	v_cvt_pk_bf16_f32 v249, v32, v33
	global_store_dwordx4 v237, v[246:249], s[54:55]
	s_add_u32 s54, s54, 0x1000
	s_addc_u32 s55, s55, 0
	s_mov_b64 s[52:53], s[42:43]
	global_load_dwordx4 v[0:3], v238, s[52:53] nt
	global_load_dwordx4 v[4:7], v238, s[52:53] offset:1024 nt
	global_load_dwordx4 v[8:11], v238, s[52:53] offset:2048 nt
	global_load_dwordx4 v[14:17], v238, s[52:53] offset:3072 nt
	s_add_u32 s52, s52, 0x10000
	s_addc_u32 s53, s53, 0
	global_load_dwordx4 v[18:21], v238, s[52:53] nt
	global_load_dwordx4 v[22:25], v238, s[52:53] offset:1024 nt
	global_load_dwordx4 v[26:29], v238, s[52:53] offset:2048 nt
	global_load_dwordx4 v[30:33], v238, s[52:53] offset:3072 nt
	s_add_u32 s52, s52, 0x10000
	s_addc_u32 s53, s53, 0
	s_waitcnt vmcnt(4)
	v_cvt_pk_bf16_f32 v242, v0, v4
	v_cvt_pk_bf16_f32 v243, v8, v14
	v_cvt_pk_bf16_f32 v244, v1, v5
	v_cvt_pk_bf16_f32 v245, v9, v15
	v_cvt_pk_bf16_f32 v246, v2, v6
	v_cvt_pk_bf16_f32 v247, v10, v16
	v_cvt_pk_bf16_f32 v248, v3, v7
	v_cvt_pk_bf16_f32 v249, v11, v17
	ds_write_b64 v239, v[242:243] offset:0
	ds_write_b64 v239, v[244:245] offset:528
	ds_write_b64 v239, v[246:247] offset:1056
	ds_write_b64 v239, v[248:249] offset:1584
	s_waitcnt vmcnt(0)
	v_cvt_pk_bf16_f32 v242, v18, v22
	v_cvt_pk_bf16_f32 v243, v26, v30
	v_cvt_pk_bf16_f32 v244, v19, v23
	v_cvt_pk_bf16_f32 v245, v27, v31
	v_cvt_pk_bf16_f32 v246, v20, v24
	v_cvt_pk_bf16_f32 v247, v28, v32
	v_cvt_pk_bf16_f32 v248, v21, v25
	v_cvt_pk_bf16_f32 v249, v29, v33
	ds_write_b64 v239, v[242:243] offset:128
	ds_write_b64 v239, v[244:245] offset:656
	ds_write_b64 v239, v[246:247] offset:1184
	ds_write_b64 v239, v[248:249] offset:1712
	global_load_dwordx4 v[0:3], v238, s[52:53] nt
	global_load_dwordx4 v[4:7], v238, s[52:53] offset:1024 nt
	global_load_dwordx4 v[8:11], v238, s[52:53] offset:2048 nt
	global_load_dwordx4 v[14:17], v238, s[52:53] offset:3072 nt
	s_add_u32 s52, s52, 0x10000
	s_addc_u32 s53, s53, 0
	global_load_dwordx4 v[18:21], v238, s[52:53] nt
	global_load_dwordx4 v[22:25], v238, s[52:53] offset:1024 nt
	global_load_dwordx4 v[26:29], v238, s[52:53] offset:2048 nt
	global_load_dwordx4 v[30:33], v238, s[52:53] offset:3072 nt
	s_add_u32 s52, s52, 0x10000
	s_addc_u32 s53, s53, 0
	s_waitcnt vmcnt(4)
	v_cvt_pk_bf16_f32 v242, v0, v4
	v_cvt_pk_bf16_f32 v243, v8, v14
	v_cvt_pk_bf16_f32 v244, v1, v5
	v_cvt_pk_bf16_f32 v245, v9, v15
	v_cvt_pk_bf16_f32 v246, v2, v6
	v_cvt_pk_bf16_f32 v247, v10, v16
	v_cvt_pk_bf16_f32 v248, v3, v7
	v_cvt_pk_bf16_f32 v249, v11, v17
	ds_write_b64 v239, v[242:243] offset:256
	ds_write_b64 v239, v[244:245] offset:784
	ds_write_b64 v239, v[246:247] offset:1312
	ds_write_b64 v239, v[248:249] offset:1840
	s_waitcnt vmcnt(0)
	v_cvt_pk_bf16_f32 v242, v18, v22
	v_cvt_pk_bf16_f32 v243, v26, v30
	v_cvt_pk_bf16_f32 v244, v19, v23
	v_cvt_pk_bf16_f32 v245, v27, v31
	v_cvt_pk_bf16_f32 v246, v20, v24
	v_cvt_pk_bf16_f32 v247, v28, v32
	v_cvt_pk_bf16_f32 v248, v21, v25
	v_cvt_pk_bf16_f32 v249, v29, v33
	ds_write_b64 v239, v[242:243] offset:384
	ds_write_b64 v239, v[244:245] offset:912
	ds_write_b64 v239, v[246:247] offset:1440
	ds_write_b64 v239, v[248:249] offset:1968
	s_waitcnt lgkmcnt(0)
	s_barrier
; __device__ __forceinline__ float ldnt(const float* p) { return __builtin_nontemporal_load(p); }
; __device__ __forceinline__ void conv_sample_kv(KP p, int l) {
;     ...
;     for (size_t i0 = gt; i0 < (size_t)128 * 64 * 256; i0 += 4 * gs) {
;         float v[4][4];
; #pragma unroll
;         for (int u = 0; u < 4; ++u) {
;             const size_t i = i0 + u * gs;
;             if (i < (size_t)128 * 64 * 256) {
;                 const int d = i & 63, h = (i >> 6) & 3, kq = (i >> 8) & 63, b = (int)(i >> 14);
; #pragma unroll
;                 for (int j = 0; j < 4; ++j) v[u][j] = ldnt(cv + ((size_t)(b * 256 + kq * 4 + j) * 4 + h) * 64 + d);
;             }
;         }
; #pragma unroll
;         for (int u = 0; u < 4; ++u) {
;             const size_t i = i0 + u * gs;
;             if (i < (size_t)128 * 64 * 256) {
;                 const int d = i & 63, h = (i >> 6) & 3, kq = (i >> 8) & 63, b = (int)(i >> 14);
;                 *(uint2*)(Vts + ((size_t)(b * 4 + h) * 64 + d) * 256 + kq * 4) = make_uint2(pack2(v[u][0], v[u][1]), pack2(v[u][2], v[u][3]));
;             }
;         }
	s_mov_b64 s[54:55], s[50:51]
	ds_read_b128 v[244:247], v240 offset:0
	s_waitcnt lgkmcnt(0)
	global_store_dwordx4 v241, v[244:247], s[54:55]
	s_add_u32 s54, s54, 0x1000
	s_addc_u32 s55, s55, 0
	ds_read_b128 v[248:251], v240 offset:4224
	s_waitcnt lgkmcnt(0)
	global_store_dwordx4 v241, v[248:251], s[54:55]
	s_add_u32 s54, s54, 0x1000
	s_addc_u32 s55, s55, 0
	ds_read_b128 v[244:247], v240 offset:8448
	s_waitcnt lgkmcnt(0)
	global_store_dwordx4 v241, v[244:247], s[54:55]
	s_add_u32 s54, s54, 0x1000
	s_addc_u32 s55, s55, 0
	ds_read_b128 v[248:251], v240 offset:12672
	s_waitcnt lgkmcnt(0)
	global_store_dwordx4 v241, v[248:251], s[54:55]
	s_add_u32 s54, s54, 0x1000
	s_addc_u32 s55, s55, 0
	ds_read_b128 v[244:247], v240 offset:16896
	s_waitcnt lgkmcnt(0)
	global_store_dwordx4 v241, v[244:247], s[54:55]
	s_add_u32 s54, s54, 0x1000
	s_addc_u32 s55, s55, 0
	ds_read_b128 v[248:251], v240 offset:21120
	s_waitcnt lgkmcnt(0)
	global_store_dwordx4 v241, v[248:251], s[54:55]
	s_add_u32 s54, s54, 0x1000
	s_addc_u32 s55, s55, 0
	ds_read_b128 v[244:247], v240 offset:25344
	s_waitcnt lgkmcnt(0)
	global_store_dwordx4 v241, v[244:247], s[54:55]
	s_add_u32 s54, s54, 0x1000
	s_addc_u32 s55, s55, 0
	ds_read_b128 v[248:251], v240 offset:29568
	s_waitcnt lgkmcnt(0)
	global_store_dwordx4 v241, v[248:251], s[54:55]
	s_add_u32 s54, s54, 0x1000
	s_addc_u32 s55, s55, 0
	s_barrier
	s_add_i32 s24, s24, s62
	s_cmpk_lt_u32 s24, 0x200
	s_cbranch_scc1 .Lconv_pair
